# norm2 pass context-row path: gvec/scale/shift loads of column groups 1-3 issued together with group 0 before the row reduction instead of serially after each store
# speedup vs baseline: 1.0055x; 1.0026x over previous
; __device__ __forceinline__ void norm_mod_pass(const float* xlat, float* xctx, const float* gvec, const float* modL, int ch_sh, int ch_sc, bf16* H, int nrows, int gw, int NGW, int lane, const bf16* x1a, const bf16* x1b, const float* P, int nsplit, const float* pgate) {
;     ...
;         for (int r = TLAT + gw; r < nrows; r += NGW) {
;             f32x4 v[4], pp_[4][11];
; #pragma unroll
;             for (int jj = 0; jj < 4; ++jj) { const int cidx = 4 * lane + 256 * jj; v[jj] = *(const f32x4*)(xctx + (size_t)(r - TLAT) * DM + cidx);
; #pragma unroll
;                 for (int s = 0; s < 11; ++s) { const int se = s < nsplit ? s : nsplit - 1; pp_[jj][s] = *(const f32x4*)(P + ((size_t)se * TCTX + (r - TLAT)) * DM + cidx); } }
;             float ss = 0.f;
; #pragma unroll
;             for (int jj = 0; jj < 4; ++jj) { const int cidx = 4 * lane + 256 * jj; f32x4 a = (f32x4){0.f, 0.f, 0.f, 0.f};
; #pragma unroll
;                 for (int s = 0; s < 11; ++s) a += pp_[jj][s] * (s < nsplit ? 1.f : 0.f);
;                 v[jj] += *(const f32x4*)(pgate + cidx) * a; *(f32x4*)(xctx + (size_t)(r - TLAT) * DM + cidx) = v[jj];
;                 ss += (v[jj].x * v[jj].x + v[jj].y * v[jj].y) + (v[jj].z * v[jj].z + v[jj].w * v[jj].w); }
.LBB0_60:
	v_lshl_add_u64 v[8:9], s[30:31], 0, v[80:81]
	v_lshl_add_u64 v[94:95], s[30:31], 0, v[76:77]
	v_lshl_add_u64 v[10:11], s[30:31], 0, v[82:83]
	v_lshl_add_u64 v[20:21], s[30:31], 0, v[84:85]
	v_lshl_add_u64 v[24:25], s[30:31], 0, v[88:89]
	v_lshl_add_u64 v[28:29], s[30:31], 0, v[90:91]
	v_lshl_add_u64 v[32:33], s[30:31], 0, v[92:93]
	v_lshl_add_u64 v[36:37], s[30:31], 0, v[86:87]
	v_lshl_add_u64 v[192:193], s[30:31], 0, v[78:79]
	global_load_dwordx4 v[0:3], v[8:9], off offset:-2048
	global_load_dwordx4 v[4:7], v[10:11], off offset:-2048
	global_load_dwordx4 v[40:43], v[20:21], off offset:-2048
	global_load_dwordx4 v[96:99], v[24:25], off offset:-2048
	global_load_dwordx4 v[100:103], v[28:29], off offset:-2048
	global_load_dwordx4 v[104:107], v[32:33], off offset:-2048
	global_load_dwordx4 v[108:111], v[36:37], off offset:-2048
	global_load_dwordx4 v[112:115], v[192:193], off offset:-2048
	global_load_dwordx4 v[116:119], v[94:95], off
	global_load_dwordx4 v[120:123], v[50:51], off
	v_mov_b32_e32 v47, v46
	global_load_dwordx4 v[124:127], v[94:95], off offset:1024
	global_load_dwordx4 v[128:131], v[8:9], off offset:-1024
	global_load_dwordx4 v[132:135], v[10:11], off offset:-1024
	global_load_dwordx4 v[136:139], v[20:21], off offset:-1024
	global_load_dwordx4 v[140:143], v[24:25], off offset:-1024
	global_load_dwordx4 v[144:147], v[28:29], off offset:-1024
	global_load_dwordx4 v[148:151], v[32:33], off offset:-1024
	global_load_dwordx4 v[152:155], v[36:37], off offset:-1024
	global_load_dwordx4 v[156:159], v[192:193], off offset:-1024
	global_load_dwordx4 v[160:163], v[8:9], off
	global_load_dwordx4 v[12:15], v[8:9], off offset:1024
	global_load_dwordx4 v[164:167], v[10:11], off
	global_load_dwordx4 v[16:19], v[10:11], off offset:1024
	global_load_dwordx4 v[168:171], v[20:21], off
	s_nop 0
	global_load_dwordx4 v[20:23], v[20:21], off offset:1024
	s_nop 0
	global_load_dwordx4 v[172:175], v[24:25], off
	s_nop 0
	global_load_dwordx4 v[24:27], v[24:25], off offset:1024
	s_nop 0
	global_load_dwordx4 v[176:179], v[28:29], off
	s_nop 0
	global_load_dwordx4 v[28:31], v[28:29], off offset:1024
	s_nop 0
	global_load_dwordx4 v[180:183], v[32:33], off
	s_nop 0
	global_load_dwordx4 v[32:35], v[32:33], off offset:1024
	s_nop 0
	global_load_dwordx4 v[184:187], v[36:37], off
	s_nop 0
	global_load_dwordx4 v[36:39], v[36:37], off offset:1024
	s_nop 0
	global_load_dwordx4 v[188:191], v[192:193], off
	global_load_dwordx4 v[8:11], v[192:193], off offset:1024
	s_add_i32 s8, s8, s60
	v_lshl_add_u64 v[76:77], v[76:77], 0, s[12:13]
	v_lshl_add_u64 v[78:79], v[78:79], 0, s[12:13]
	v_lshl_add_u64 v[80:81], v[80:81], 0, s[12:13]
	v_lshl_add_u64 v[82:83], v[82:83], 0, s[12:13]
	v_lshl_add_u64 v[84:85], v[84:85], 0, s[12:13]
	v_lshl_add_u64 v[86:87], v[86:87], 0, s[12:13]
	v_lshl_add_u64 v[88:89], v[88:89], 0, s[12:13]
	v_lshl_add_u64 v[90:91], v[90:91], 0, s[12:13]
	v_lshl_add_u64 v[92:93], v[92:93], 0, s[12:13]
	s_waitcnt vmcnt(0)
	v_pk_fma_f32 v[14:15], v[46:47], v[14:15], 0 op_sel_hi:[1,1,0]
	v_pk_fma_f32 v[12:13], v[48:49], v[12:13], 0 op_sel_hi:[1,1,0]
	s_waitcnt vmcnt(12)
	v_pk_fma_f32 v[14:15], v[46:47], v[18:19], v[14:15]
	v_pk_fma_f32 v[2:3], v[46:47], v[2:3], 0 op_sel_hi:[1,1,0]
	v_pk_fma_f32 v[0:1], v[48:49], v[0:1], 0 op_sel_hi:[1,1,0]
	v_pk_fma_f32 v[2:3], v[46:47], v[6:7], v[2:3]
	v_pk_fma_f32 v[0:1], v[48:49], v[4:5], v[0:1]
	v_pk_fma_f32 v[2:3], v[46:47], v[42:43], v[2:3]
	v_pk_fma_f32 v[0:1], v[48:49], v[40:41], v[0:1]
	v_pk_fma_f32 v[2:3], v[46:47], v[98:99], v[2:3]
	v_pk_fma_f32 v[0:1], v[48:49], v[96:97], v[0:1]
	v_pk_fma_f32 v[2:3], v[46:47], v[102:103], v[2:3]
	v_pk_fma_f32 v[0:1], v[48:49], v[100:101], v[0:1]
	v_pk_fma_f32 v[2:3], v[46:47], v[106:107], v[2:3]
	v_pk_fma_f32 v[0:1], v[48:49], v[104:105], v[0:1]
	v_pk_fma_f32 v[2:3], v[46:47], v[110:111], v[2:3]
	v_pk_fma_f32 v[0:1], v[48:49], v[108:109], v[0:1]
	v_pk_fma_f32 v[2:3], v[46:47], v[114:115], v[2:3]
	v_pk_fma_f32 v[0:1], v[48:49], v[112:113], v[0:1]
	v_pk_fma_f32 v[2:3], v[114:115], 0, v[2:3] op_sel_hi:[1,0,1]
	v_pk_fma_f32 v[0:1], v[112:113], 0, v[0:1] op_sel_hi:[1,0,1]
	v_pk_fma_f32 v[2:3], v[114:115], 0, v[2:3] op_sel_hi:[1,0,1]
	v_pk_fma_f32 v[0:1], v[112:113], 0, v[0:1] op_sel_hi:[1,0,1]
	v_pk_fma_f32 v[2:3], v[114:115], 0, v[2:3] op_sel_hi:[1,0,1]
	v_pk_fma_f32 v[0:1], v[112:113], 0, v[0:1] op_sel_hi:[1,0,1]
	v_pk_fma_f32 v[2:3], v[2:3], v[122:123], v[118:119]
	v_pk_fma_f32 v[0:1], v[0:1], v[120:121], v[116:117]
	global_store_dwordx4 v[94:95], v[0:3], off
	global_load_dwordx4 v[4:7], v[52:53], off
	global_load_dwordx4 v[40:43], v[94:95], off offset:2048
	v_pk_fma_f32 v[96:97], v[46:47], v[130:131], 0 op_sel_hi:[1,1,0]
	v_pk_fma_f32 v[98:99], v[48:49], v[128:129], 0 op_sel_hi:[1,1,0]
	v_pk_fma_f32 v[96:97], v[46:47], v[134:135], v[96:97]
	v_pk_fma_f32 v[98:99], v[48:49], v[132:133], v[98:99]
	v_pk_fma_f32 v[96:97], v[46:47], v[138:139], v[96:97]
	v_pk_fma_f32 v[98:99], v[48:49], v[136:137], v[98:99]
	v_pk_fma_f32 v[96:97], v[46:47], v[142:143], v[96:97]
	v_pk_fma_f32 v[98:99], v[48:49], v[140:141], v[98:99]
	v_pk_fma_f32 v[96:97], v[46:47], v[146:147], v[96:97]
	v_pk_fma_f32 v[98:99], v[48:49], v[144:145], v[98:99]
	v_pk_fma_f32 v[96:97], v[46:47], v[150:151], v[96:97]
	v_pk_fma_f32 v[98:99], v[48:49], v[148:149], v[98:99]
	v_pk_fma_f32 v[96:97], v[46:47], v[154:155], v[96:97]
	v_pk_fma_f32 v[98:99], v[48:49], v[152:153], v[98:99]
	v_pk_fma_f32 v[96:97], v[46:47], v[158:159], v[96:97]
	v_pk_fma_f32 v[98:99], v[48:49], v[156:157], v[98:99]
	v_pk_fma_f32 v[96:97], v[158:159], 0, v[96:97] op_sel_hi:[1,0,1]
	v_pk_fma_f32 v[98:99], v[156:157], 0, v[98:99] op_sel_hi:[1,0,1]
	v_pk_fma_f32 v[96:97], v[158:159], 0, v[96:97] op_sel_hi:[1,0,1]
	v_pk_fma_f32 v[98:99], v[156:157], 0, v[98:99] op_sel_hi:[1,0,1]
	v_pk_fma_f32 v[96:97], v[158:159], 0, v[96:97] op_sel_hi:[1,0,1]
	v_pk_fma_f32 v[98:99], v[156:157], 0, v[98:99] op_sel_hi:[1,0,1]
	v_pk_fma_f32 v[104:105], v[46:47], v[162:163], 0 op_sel_hi:[1,1,0]
	v_pk_fma_f32 v[106:107], v[48:49], v[160:161], 0 op_sel_hi:[1,1,0]
	v_pk_fma_f32 v[104:105], v[46:47], v[166:167], v[104:105]
	v_pk_fma_f32 v[106:107], v[48:49], v[164:165], v[106:107]
	s_waitcnt vmcnt(14)
; __device__ __forceinline__ void norm_mod_pass(const float* xlat, float* xctx, const float* gvec, const float* modL, int ch_sh, int ch_sc, bf16* H, int nrows, int gw, int NGW, int lane, const bf16* x1a, const bf16* x1b, const float* P, int nsplit, const float* pgate) {
;     ...
;             for (int jj = 0; jj < 4; ++jj) { const int cidx = 4 * lane + 256 * jj; f32x4 a = (f32x4){0.f, 0.f, 0.f, 0.f};
; #pragma unroll
;                 for (int s = 0; s < 11; ++s) a += pp_[jj][s] * (s < nsplit ? 1.f : 0.f);
;                 v[jj] += *(const f32x4*)(pgate + cidx) * a; *(f32x4*)(xctx + (size_t)(r - TLAT) * DM + cidx) = v[jj];
;                 ss += (v[jj].x * v[jj].x + v[jj].y * v[jj].y) + (v[jj].z * v[jj].z + v[jj].w * v[jj].w); }
;             ss = wave_sum(ss); const float rs = 1.0f / sqrtf(ss * (1.0f / DM) + EPSN);
; #pragma unroll
;             for (int jj = 0; jj < 4; ++jj) { const int cidx = 4 * lane + 256 * jj; const f32x4 gmv = *(const f32x4*)(gvec + cidx) * (*(const f32x4*)(sc + cidx) + 1.0f);
;                 const f32x4 o = v[jj] * rs * gmv + *(const f32x4*)(sh + cidx); v2u w; w.x = pk2(o.x, o.y); w.y = pk2(o.z, o.w);
;                 *(v2u*)(H + (size_t)r * DM + cidx) = w; }
	v_pk_fma_f32 v[104:105], v[46:47], v[170:171], v[104:105]
	v_pk_fma_f32 v[106:107], v[48:49], v[168:169], v[106:107]
	s_waitcnt vmcnt(12)
	v_pk_fma_f32 v[104:105], v[46:47], v[174:175], v[104:105]
	v_pk_fma_f32 v[106:107], v[48:49], v[172:173], v[106:107]
	s_waitcnt vmcnt(10)
	v_pk_fma_f32 v[104:105], v[46:47], v[178:179], v[104:105]
	v_pk_fma_f32 v[106:107], v[48:49], v[176:177], v[106:107]
	s_waitcnt vmcnt(8)
	v_pk_fma_f32 v[104:105], v[46:47], v[182:183], v[104:105]
	v_pk_fma_f32 v[106:107], v[48:49], v[180:181], v[106:107]
	s_waitcnt vmcnt(6)
	v_pk_fma_f32 v[104:105], v[46:47], v[186:187], v[104:105]
	v_pk_fma_f32 v[106:107], v[48:49], v[184:185], v[106:107]
	s_waitcnt vmcnt(4)
	v_pk_fma_f32 v[104:105], v[46:47], v[190:191], v[104:105]
	v_pk_fma_f32 v[106:107], v[48:49], v[188:189], v[106:107]
	v_pk_fma_f32 v[104:105], v[190:191], 0, v[104:105] op_sel_hi:[1,0,1]
	v_pk_fma_f32 v[106:107], v[188:189], 0, v[106:107] op_sel_hi:[1,0,1]
	v_pk_fma_f32 v[104:105], v[190:191], 0, v[104:105] op_sel_hi:[1,0,1]
	v_pk_fma_f32 v[106:107], v[188:189], 0, v[106:107] op_sel_hi:[1,0,1]
	v_pk_fma_f32 v[104:105], v[190:191], 0, v[104:105] op_sel_hi:[1,0,1]
	v_pk_fma_f32 v[106:107], v[188:189], 0, v[106:107] op_sel_hi:[1,0,1]
	v_pk_fma_f32 v[12:13], v[48:49], v[16:17], v[12:13]
	v_pk_fma_f32 v[14:15], v[46:47], v[22:23], v[14:15]
	v_pk_fma_f32 v[12:13], v[48:49], v[20:21], v[12:13]
	v_pk_fma_f32 v[14:15], v[46:47], v[26:27], v[14:15]
	v_pk_fma_f32 v[12:13], v[48:49], v[24:25], v[12:13]
	v_pk_fma_f32 v[14:15], v[46:47], v[30:31], v[14:15]
	v_pk_fma_f32 v[12:13], v[48:49], v[28:29], v[12:13]
	v_pk_fma_f32 v[14:15], v[46:47], v[34:35], v[14:15]
	v_pk_fma_f32 v[12:13], v[48:49], v[32:33], v[12:13]
	v_pk_fma_f32 v[14:15], v[46:47], v[38:39], v[14:15]
	v_pk_fma_f32 v[12:13], v[48:49], v[36:37], v[12:13]
	s_waitcnt vmcnt(3)
	v_pk_fma_f32 v[14:15], v[46:47], v[10:11], v[14:15]
	v_pk_fma_f32 v[12:13], v[48:49], v[8:9], v[12:13]
	v_pk_fma_f32 v[14:15], v[10:11], 0, v[14:15] op_sel_hi:[1,0,1]
	v_pk_fma_f32 v[12:13], v[8:9], 0, v[12:13] op_sel_hi:[1,0,1]
	v_pk_fma_f32 v[14:15], v[10:11], 0, v[14:15] op_sel_hi:[1,0,1]
	v_pk_fma_f32 v[12:13], v[8:9], 0, v[12:13] op_sel_hi:[1,0,1]
	v_pk_fma_f32 v[10:11], v[10:11], 0, v[14:15] op_sel_hi:[1,0,1]
	v_pk_fma_f32 v[8:9], v[8:9], 0, v[12:13] op_sel_hi:[1,0,1]
	v_pk_mul_f32 v[12:13], v[2:3], v[2:3]
	v_pk_mul_f32 v[14:15], v[0:1], v[0:1]
	s_waitcnt vmcnt(1)
	v_pk_fma_f32 v[6:7], v[96:97], v[6:7], v[126:127]
	v_pk_fma_f32 v[4:5], v[98:99], v[4:5], v[124:125]
	global_store_dwordx4 v[94:95], v[4:7], off offset:1024
	global_load_dwordx4 v[96:99], v[54:55], off
	global_load_dwordx4 v[100:103], v[94:95], off offset:3072
	v_pk_mov_b32 v[16:17], v[14:15], v[12:13] op_sel:[1,0]
	v_mov_b32_e32 v15, v13
	v_pk_add_f32 v[12:13], v[14:15], v[16:17]
	v_pk_mul_f32 v[14:15], v[4:5], v[4:5]
	v_pk_add_f32 v[24:25], v[12:13], v[12:13] op_sel:[0,1] op_sel_hi:[1,0]
	v_pk_mul_f32 v[12:13], v[6:7], v[6:7]
	s_waitcnt vmcnt(1)
	v_pk_fma_f32 v[42:43], v[104:105], v[98:99], v[42:43]
	v_pk_fma_f32 v[40:41], v[106:107], v[96:97], v[40:41]
	global_store_dwordx4 v[94:95], v[40:43], off offset:2048
	global_load_dwordx4 v[96:99], v[56:57], off
	v_pk_mov_b32 v[16:17], v[14:15], v[12:13] op_sel:[1,0]
	v_mov_b32_e32 v15, v13
	v_pk_add_f32 v[12:13], v[14:15], v[16:17]
	v_mul_f32_e32 v14, v43, v43
	v_pk_add_f32 v[26:27], v[12:13], v[12:13] op_sel:[0,1] op_sel_hi:[1,0]
	v_mul_f32_e32 v12, v41, v41
	v_pk_fma_f32 v[28:29], v[40:41], v[40:41], v[12:13] op_sel_hi:[1,1,0]
	v_pk_fma_f32 v[30:31], v[42:43], v[42:43], v[14:15] op_sel_hi:[1,1,0]
	v_lshl_add_u64 v[104:105], s[30:31], 0, v[74:75]
	v_add_co_u32_e32 v104, vcc, s72, v104
	v_lshl_add_u64 v[74:75], v[74:75], 0, s[10:11]
	s_nop 0
	v_addc_co_u32_e32 v105, vcc, 0, v105, vcc
	s_waitcnt vmcnt(0)
	v_pk_fma_f32 v[10:11], v[10:11], v[98:99], v[102:103]
	v_pk_fma_f32 v[8:9], v[8:9], v[96:97], v[100:101]
	global_store_dwordx4 v[94:95], v[8:11], off offset:3072
	global_load_dwordx4 v[12:15], v[58:59], off
	global_load_dwordx4 v[16:19], v[44:45], off
	global_load_dwordx4 v[20:23], v[60:61], off
	global_load_dwordx4 v[128:131], v[62:63], off
	global_load_dwordx4 v[132:135], v[44:45], off offset:1024
	global_load_dwordx4 v[136:139], v[64:65], off
	global_load_dwordx4 v[140:143], v[66:67], off
	global_load_dwordx4 v[144:147], v[44:45], off offset:2048
	global_load_dwordx4 v[148:151], v[68:69], off
	global_load_dwordx4 v[152:155], v[70:71], off
	global_load_dwordx4 v[156:159], v[44:45], off offset:3072
	global_load_dwordx4 v[160:163], v[72:73], off
	v_mul_f32_e32 v25, v8, v8
	v_mul_f32_e32 v27, v9, v9
	v_mul_f32_e32 v31, v10, v10
	v_mul_f32_e32 v29, v11, v11
	v_pk_add_f32 v[24:25], v[24:25], v[26:27]
	v_pk_add_f32 v[26:27], v[28:29], v[30:31]
	s_waitcnt vmcnt(11)
; __device__ __forceinline__ void norm_mod_pass(const float* xlat, float* xctx, const float* gvec, const float* modL, int ch_sh, int ch_sc, bf16* H, int nrows, int gw, int NGW, int lane, const bf16* x1a, const bf16* x1b, const float* P, int nsplit, const float* pgate) {
;     ...
;             ss = wave_sum(ss); const float rs = 1.0f / sqrtf(ss * (1.0f / DM) + EPSN);
; #pragma unroll
;             for (int jj = 0; jj < 4; ++jj) { const int cidx = 4 * lane + 256 * jj; const f32x4 gmv = *(const f32x4*)(gvec + cidx) * (*(const f32x4*)(sc + cidx) + 1.0f);
;                 const f32x4 o = v[jj] * rs * gmv + *(const f32x4*)(sh + cidx); v2u w; w.x = pk2(o.x, o.y); w.y = pk2(o.z, o.w);
;                 *(v2u*)(H + (size_t)r * DM + cidx) = w; }
	v_pk_add_f32 v[14:15], v[14:15], 1.0 op_sel_hi:[1,0]
	v_pk_add_f32 v[24:25], v[24:25], v[26:27]
	v_pk_add_f32 v[12:13], v[12:13], 1.0 op_sel_hi:[1,0]
	v_add_f32_e32 v24, v24, v25
	s_waitcnt vmcnt(10)
	v_pk_mul_f32 v[14:15], v[18:19], v[14:15]
	v_pk_mul_f32 v[12:13], v[16:17], v[12:13]
	v_add_f32_dpp v24, v24, v24 quad_perm:[1,0,3,2] row_mask:0xf bank_mask:0xf bound_ctrl:1
	s_nop 1
	v_add_f32_dpp v24, v24, v24 quad_perm:[2,3,0,1] row_mask:0xf bank_mask:0xf bound_ctrl:1
	s_nop 1
	v_add_f32_dpp v24, v24, v24 row_half_mirror row_mask:0xf bank_mask:0xf bound_ctrl:1
	s_nop 1
	v_add_f32_dpp v24, v24, v24 row_mirror row_mask:0xf bank_mask:0xf bound_ctrl:1
	s_nop 0
	v_readlane_b32 s2, v24, 16
	v_readlane_b32 s3, v24, 48
	v_readlane_b32 s0, v24, 0
	v_readlane_b32 s1, v24, 32
	v_mov_b32_e32 v24, s2
	v_mov_b32_e32 v25, s3
	v_pk_add_f32 v[24:25], s[0:1], v[24:25]
	s_nop 0
	v_add_f32_e32 v24, v24, v25
	v_fmamk_f32 v24, v24, 0x3a800000, v243
	v_mul_f32_e32 v25, 0x4f800000, v24
	v_cmp_gt_f32_e32 vcc, s71, v24
	s_nop 1
	v_cndmask_b32_e32 v24, v24, v25, vcc
	v_sqrt_f32_e32 v25, v24
	s_nop 0
	v_add_u32_e32 v26, -1, v25
	v_add_u32_e32 v27, 1, v25
	v_fma_f32 v28, -v26, v25, v24
	v_fma_f32 v29, -v27, v25, v24
	v_cmp_ge_f32_e64 s[4:5], 0, v28
	s_nop 1
	v_cndmask_b32_e64 v25, v25, v26, s[4:5]
	v_cmp_lt_f32_e64 s[4:5], 0, v29
	s_nop 1
	v_cndmask_b32_e64 v25, v25, v27, s[4:5]
	v_mul_f32_e32 v26, 0x37800000, v25
	v_cndmask_b32_e32 v25, v25, v26, vcc
	v_cmp_class_f32_e32 vcc, v24, v244
	s_nop 1
	v_cndmask_b32_e32 v24, v25, v24, vcc
	v_div_scale_f32 v25, s[0:1], v24, v24, 1.0
	v_rcp_f32_e32 v27, v25
	v_div_scale_f32 v26, vcc, 1.0, v24, 1.0
	v_readlane_b32 s0, v254, 15
	v_fma_f32 v28, -v25, v27, 1.0
	v_fmac_f32_e32 v27, v28, v27
	v_mul_f32_e32 v28, v26, v27
	v_fma_f32 v29, -v25, v28, v26
	v_fmac_f32_e32 v28, v29, v27
	v_fma_f32 v25, -v25, v28, v26
	v_div_fmas_f32 v25, v25, v27, v28
	v_div_fixup_f32 v24, v25, v24, 1.0
	v_pk_mul_f32 v[0:1], v[0:1], v[24:25] op_sel_hi:[1,0]
	v_pk_mul_f32 v[2:3], v[2:3], v[24:25] op_sel_hi:[1,0]
	s_waitcnt vmcnt(9)
	v_pk_fma_f32 v[0:1], v[12:13], v[0:1], v[20:21]
	v_pk_fma_f32 v[2:3], v[14:15], v[2:3], v[22:23]
	v_cvt_pk_bf16_f32 v0, v0, v1
	v_cvt_pk_bf16_f32 v1, v2, v3
	global_store_dwordx2 v[104:105], v[0:1], off
	s_nop 0
	v_pk_mul_f32 v[4:5], v[4:5], v[24:25] op_sel_hi:[1,0]
	v_pk_mul_f32 v[6:7], v[6:7], v[24:25] op_sel_hi:[1,0]
	v_pk_mul_f32 v[8:9], v[8:9], v[24:25] op_sel_hi:[1,0]
	v_pk_mul_f32 v[10:11], v[10:11], v[24:25] op_sel_hi:[1,0]
	s_cmp_ge_i32 s8, s0
	s_waitcnt vmcnt(8)
	v_pk_add_f32 v[2:3], v[130:131], 1.0 op_sel_hi:[1,0]
	v_pk_add_f32 v[0:1], v[128:129], 1.0 op_sel_hi:[1,0]
	s_waitcnt vmcnt(7)
	v_pk_mul_f32 v[2:3], v[134:135], v[2:3]
	v_pk_mul_f32 v[0:1], v[132:133], v[0:1]
	s_waitcnt vmcnt(6)
	v_pk_fma_f32 v[2:3], v[2:3], v[6:7], v[138:139]
	v_pk_fma_f32 v[0:1], v[0:1], v[4:5], v[136:137]
	v_pk_mul_f32 v[16:17], v[40:41], v[24:25] op_sel_hi:[1,0]
	v_cvt_pk_bf16_f32 v0, v0, v1
	v_cvt_pk_bf16_f32 v1, v2, v3
	global_store_dwordx2 v[104:105], v[0:1], off offset:512
	s_nop 0
	v_pk_mul_f32 v[18:19], v[42:43], v[24:25] op_sel_hi:[1,0]
	s_waitcnt vmcnt(5)
	v_pk_add_f32 v[2:3], v[142:143], 1.0 op_sel_hi:[1,0]
	v_pk_add_f32 v[0:1], v[140:141], 1.0 op_sel_hi:[1,0]
	s_waitcnt vmcnt(4)
	v_pk_mul_f32 v[2:3], v[146:147], v[2:3]
	v_pk_mul_f32 v[0:1], v[144:145], v[0:1]
	s_waitcnt vmcnt(3)
	v_pk_fma_f32 v[2:3], v[18:19], v[2:3], v[150:151]
	v_pk_fma_f32 v[0:1], v[16:17], v[0:1], v[148:149]
	s_nop 0
	v_cvt_pk_bf16_f32 v0, v0, v1
	v_cvt_pk_bf16_f32 v1, v2, v3
	global_store_dwordx2 v[104:105], v[0:1], off offset:1024
	s_nop 0
	s_waitcnt vmcnt(2)
	v_pk_add_f32 v[2:3], v[154:155], 1.0 op_sel_hi:[1,0]
	v_pk_add_f32 v[0:1], v[152:153], 1.0 op_sel_hi:[1,0]
	s_waitcnt vmcnt(1)
	v_pk_mul_f32 v[2:3], v[158:159], v[2:3]
	v_pk_mul_f32 v[0:1], v[156:157], v[0:1]
	s_waitcnt vmcnt(0)
	v_pk_fma_f32 v[2:3], v[10:11], v[2:3], v[162:163]
	v_pk_fma_f32 v[0:1], v[8:9], v[0:1], v[160:161]
	s_nop 0
	v_cvt_pk_bf16_f32 v0, v0, v1
	v_cvt_pk_bf16_f32 v1, v2, v3
	global_store_dwordx2 v[104:105], v[0:1], off offset:1536
	s_cbranch_scc0 .LBB0_60
